# adaLN partial-GEMV loop in pre_work: the 16 weight-row loads of each unrolled iteration are issued together into v80-v143 with counted vmcnt waits (were load/wait/FMA serialized, 32 round trips per it
# speedup vs baseline: 1.0353x; 1.0353x over previous
.LBB0_531:
	v_lshl_add_u64 v[46:47], v[44:45], 0, s[8:9]
	global_load_dwordx4 v[80:83], v[46:47], off nt
	v_add_co_u32_e32 v84, vcc, 0x6000, v46
	s_nop 1
	v_addc_co_u32_e32 v85, vcc, 0, v47, vcc
	global_load_dwordx4 v[84:87], v[84:85], off nt
	v_add_co_u32_e32 v88, vcc, 0xc000, v46
	s_nop 1
	v_addc_co_u32_e32 v89, vcc, 0, v47, vcc
	global_load_dwordx4 v[88:91], v[88:89], off nt
	v_add_co_u32_e32 v92, vcc, 0x12000, v46
	s_nop 1
	v_addc_co_u32_e32 v93, vcc, 0, v47, vcc
	global_load_dwordx4 v[92:95], v[92:93], off nt
	v_add_co_u32_e32 v96, vcc, 0x18000, v46
	s_nop 1
	v_addc_co_u32_e32 v97, vcc, 0, v47, vcc
	global_load_dwordx4 v[96:99], v[96:97], off nt
	v_add_co_u32_e32 v100, vcc, 0x1e000, v46
	s_nop 1
	v_addc_co_u32_e32 v101, vcc, 0, v47, vcc
	global_load_dwordx4 v[100:103], v[100:101], off nt
	v_add_co_u32_e32 v104, vcc, 0x24000, v46
	s_nop 1
	v_addc_co_u32_e32 v105, vcc, 0, v47, vcc
	global_load_dwordx4 v[104:107], v[104:105], off nt
	v_add_co_u32_e32 v108, vcc, 0x2a000, v46
	s_nop 1
	v_addc_co_u32_e32 v109, vcc, 0, v47, vcc
	global_load_dwordx4 v[108:111], v[108:109], off nt
	v_add_co_u32_e32 v112, vcc, 0x30000, v46
	s_nop 1
	v_addc_co_u32_e32 v113, vcc, 0, v47, vcc
	global_load_dwordx4 v[112:115], v[112:113], off nt
	v_add_co_u32_e32 v116, vcc, 0x36000, v46
	s_nop 1
	v_addc_co_u32_e32 v117, vcc, 0, v47, vcc
	global_load_dwordx4 v[116:119], v[116:117], off nt
	v_add_co_u32_e32 v120, vcc, 0x3c000, v46
	s_nop 1
	v_addc_co_u32_e32 v121, vcc, 0, v47, vcc
	global_load_dwordx4 v[120:123], v[120:121], off nt
	v_add_co_u32_e32 v124, vcc, 0x42000, v46
	s_nop 1
	v_addc_co_u32_e32 v125, vcc, 0, v47, vcc
	global_load_dwordx4 v[124:127], v[124:125], off nt
	v_add_co_u32_e32 v128, vcc, 0x48000, v46
	s_nop 1
	v_addc_co_u32_e32 v129, vcc, 0, v47, vcc
	global_load_dwordx4 v[128:131], v[128:129], off nt
	v_add_co_u32_e32 v132, vcc, 0x4e000, v46
	s_nop 1
	v_addc_co_u32_e32 v133, vcc, 0, v47, vcc
	global_load_dwordx4 v[132:135], v[132:133], off nt
	v_add_co_u32_e32 v136, vcc, 0x54000, v46
	s_nop 1
	v_addc_co_u32_e32 v137, vcc, 0, v47, vcc
	global_load_dwordx4 v[136:139], v[136:137], off nt
	v_add_co_u32_e32 v140, vcc, 0x5a000, v46
	s_nop 1
	v_addc_co_u32_e32 v141, vcc, 0, v47, vcc
	global_load_dwordx4 v[140:143], v[140:141], off nt
	s_waitcnt vmcnt(15)
	v_mov_b64_e32 v[48:49], v[80:81]
	v_mov_b64_e32 v[50:51], v[82:83]
	ds_read_b128 v[58:61], v43
	ds_read_b128 v[28:31], v43 offset:16
	ds_read_b128 v[24:27], v43 offset:32
	ds_read_b128 v[20:23], v43 offset:48
	s_mov_b32 s5, 0xc000
	s_add_u32 s8, s8, 0x60000
	s_addc_u32 s9, s9, 0
	s_cmp_eq_u32 s8, 0xc0000
	s_waitcnt lgkmcnt(3)
	v_pk_fma_f32 v[62:63], v[50:51], v[58:59], v[2:3] op_sel_hi:[1,0,1]
	v_pk_fma_f32 v[64:65], v[48:49], v[58:59], v[0:1] op_sel_hi:[1,0,1]
	ds_read_b128 v[0:3], v43 offset:1024
	s_waitcnt lgkmcnt(0)
	v_pk_fma_f32 v[66:67], v[50:51], v[0:1], v[6:7] op_sel_hi:[1,0,1]
	v_pk_fma_f32 v[68:69], v[48:49], v[0:1], v[4:5] op_sel_hi:[1,0,1]
	ds_read_b128 v[4:7], v43 offset:2048
	s_waitcnt lgkmcnt(0)
	v_pk_fma_f32 v[70:71], v[50:51], v[4:5], v[10:11] op_sel_hi:[1,0,1]
	v_pk_fma_f32 v[72:73], v[48:49], v[4:5], v[8:9] op_sel_hi:[1,0,1]
	ds_read_b128 v[8:11], v43 offset:3072
	s_waitcnt lgkmcnt(0)
	v_pk_fma_f32 v[74:75], v[50:51], v[8:9], v[14:15] op_sel_hi:[1,0,1]
	v_pk_fma_f32 v[76:77], v[48:49], v[8:9], v[12:13] op_sel_hi:[1,0,1]
	ds_read_b128 v[12:15], v43 offset:4096
	s_waitcnt lgkmcnt(0)
	v_pk_fma_f32 v[48:49], v[48:49], v[12:13], v[16:17] op_sel_hi:[1,0,1]
	v_add_co_u32_e32 v16, vcc, s71, v46
	v_pk_fma_f32 v[50:51], v[50:51], v[12:13], v[18:19] op_sel_hi:[1,0,1]
	s_nop 0
	v_addc_co_u32_e32 v17, vcc, 0, v47, vcc
	s_waitcnt vmcnt(14)
	v_mov_b64_e32 v[16:17], v[84:85]
	v_mov_b64_e32 v[18:19], v[86:87]
	v_pk_fma_f32 v[64:65], v[16:17], v[58:59], v[64:65] op_sel:[0,1,0]
	v_pk_fma_f32 v[58:59], v[18:19], v[58:59], v[62:63] op_sel:[0,1,0]
	v_pk_fma_f32 v[62:63], v[16:17], v[0:1], v[68:69] op_sel:[0,1,0]
	v_pk_fma_f32 v[0:1], v[18:19], v[0:1], v[66:67] op_sel:[0,1,0]
	v_pk_fma_f32 v[66:67], v[16:17], v[4:5], v[72:73] op_sel:[0,1,0]
	v_pk_fma_f32 v[68:69], v[16:17], v[8:9], v[76:77] op_sel:[0,1,0]
	v_pk_fma_f32 v[48:49], v[16:17], v[12:13], v[48:49] op_sel:[0,1,0]
	v_add_co_u32_e32 v16, vcc, s5, v46
	v_pk_fma_f32 v[4:5], v[18:19], v[4:5], v[70:71] op_sel:[0,1,0]
	s_nop 0
	v_addc_co_u32_e32 v17, vcc, 0, v47, vcc
	v_pk_fma_f32 v[8:9], v[18:19], v[8:9], v[74:75] op_sel:[0,1,0]
	v_pk_fma_f32 v[12:13], v[18:19], v[12:13], v[50:51] op_sel:[0,1,0]
	s_waitcnt vmcnt(13)
	v_mov_b64_e32 v[16:17], v[88:89]
	v_mov_b64_e32 v[18:19], v[90:91]
	s_mov_b32 s5, 0x12000
	v_pk_fma_f32 v[50:51], v[18:19], v[60:61], v[58:59] op_sel_hi:[1,0,1]
	v_pk_fma_f32 v[58:59], v[16:17], v[60:61], v[64:65] op_sel_hi:[1,0,1]
	v_pk_fma_f32 v[70:71], v[16:17], v[2:3], v[62:63] op_sel_hi:[1,0,1]
	v_pk_fma_f32 v[66:67], v[16:17], v[6:7], v[66:67] op_sel_hi:[1,0,1]
	v_pk_fma_f32 v[68:69], v[16:17], v[10:11], v[68:69] op_sel_hi:[1,0,1]
	v_pk_fma_f32 v[72:73], v[16:17], v[14:15], v[48:49] op_sel_hi:[1,0,1]
	v_add_co_u32_e32 v16, vcc, s5, v46
	v_pk_fma_f32 v[0:1], v[18:19], v[2:3], v[0:1] op_sel_hi:[1,0,1]
	s_nop 0
	v_addc_co_u32_e32 v17, vcc, 0, v47, vcc
	s_waitcnt vmcnt(12)
	v_mov_b64_e32 v[62:63], v[92:93]
	v_mov_b64_e32 v[64:65], v[94:95]
	v_mov_b32_e32 v2, v61
	v_pk_fma_f32 v[4:5], v[18:19], v[6:7], v[4:5] op_sel_hi:[1,0,1]
	v_pk_fma_f32 v[8:9], v[18:19], v[10:11], v[8:9] op_sel_hi:[1,0,1]
	v_pk_fma_f32 v[12:13], v[18:19], v[14:15], v[12:13] op_sel_hi:[1,0,1]
	s_mov_b32 s5, 0x18000
	v_pk_fma_f32 v[60:61], v[64:65], v[2:3], v[50:51] op_sel_hi:[1,0,1]
	v_pk_fma_f32 v[58:59], v[62:63], v[2:3], v[58:59] op_sel_hi:[1,0,1]
	v_mov_b32_e32 v2, v3
	v_pk_fma_f32 v[48:49], v[64:65], v[2:3], v[0:1] op_sel_hi:[1,0,1]
	v_mov_b32_e32 v0, v7
	v_pk_fma_f32 v[16:17], v[64:65], v[0:1], v[4:5] op_sel_hi:[1,0,1]
	v_pk_fma_f32 v[18:19], v[62:63], v[0:1], v[66:67] op_sel_hi:[1,0,1]
	v_mov_b32_e32 v0, v11
	v_pk_fma_f32 v[8:9], v[64:65], v[0:1], v[8:9] op_sel_hi:[1,0,1]
	v_pk_fma_f32 v[10:11], v[62:63], v[0:1], v[68:69] op_sel_hi:[1,0,1]
	v_mov_b32_e32 v0, v15
	v_pk_fma_f32 v[4:5], v[64:65], v[0:1], v[12:13] op_sel_hi:[1,0,1]
	v_pk_fma_f32 v[6:7], v[62:63], v[0:1], v[72:73] op_sel_hi:[1,0,1]
	v_add_co_u32_e32 v0, vcc, s5, v46
	v_pk_fma_f32 v[50:51], v[62:63], v[2:3], v[70:71] op_sel_hi:[1,0,1]
	s_nop 0
	v_addc_co_u32_e32 v1, vcc, 0, v47, vcc
	s_waitcnt vmcnt(11)
	v_mov_b64_e32 v[0:1], v[96:97]
	v_mov_b64_e32 v[2:3], v[98:99]
	s_mov_b32 s5, 0x1e000
	v_pk_fma_f32 v[12:13], v[2:3], v[28:29], v[60:61] op_sel_hi:[1,0,1]
	v_pk_fma_f32 v[14:15], v[0:1], v[28:29], v[58:59] op_sel_hi:[1,0,1]
	ds_read_b128 v[58:61], v43 offset:1040
	s_waitcnt lgkmcnt(0)
	v_pk_fma_f32 v[62:63], v[2:3], v[58:59], v[48:49] op_sel_hi:[1,0,1]
	v_pk_fma_f32 v[64:65], v[0:1], v[58:59], v[50:51] op_sel_hi:[1,0,1]
	ds_read_b128 v[48:51], v43 offset:2064
	s_waitcnt lgkmcnt(0)
	v_pk_fma_f32 v[66:67], v[2:3], v[48:49], v[16:17] op_sel_hi:[1,0,1]
	v_pk_fma_f32 v[68:69], v[0:1], v[48:49], v[18:19] op_sel_hi:[1,0,1]
	ds_read_b128 v[16:19], v43 offset:3088
	s_waitcnt lgkmcnt(0)
	v_pk_fma_f32 v[70:71], v[2:3], v[16:17], v[8:9] op_sel_hi:[1,0,1]
	v_pk_fma_f32 v[72:73], v[0:1], v[16:17], v[10:11] op_sel_hi:[1,0,1]
	ds_read_b128 v[8:11], v43 offset:4112
	s_waitcnt lgkmcnt(0)
	v_pk_fma_f32 v[6:7], v[0:1], v[8:9], v[6:7] op_sel_hi:[1,0,1]
	v_add_co_u32_e32 v0, vcc, s5, v46
	v_pk_fma_f32 v[4:5], v[2:3], v[8:9], v[4:5] op_sel_hi:[1,0,1]
	s_nop 0
	v_addc_co_u32_e32 v1, vcc, 0, v47, vcc
	s_waitcnt vmcnt(10)
	v_mov_b64_e32 v[0:1], v[100:101]
	v_mov_b64_e32 v[2:3], v[102:103]
	s_mov_b32 s5, 0x24000
	v_pk_fma_f32 v[12:13], v[2:3], v[28:29], v[12:13] op_sel:[0,1,0]
	v_pk_fma_f32 v[14:15], v[0:1], v[28:29], v[14:15] op_sel:[0,1,0]
	v_pk_fma_f32 v[28:29], v[2:3], v[58:59], v[62:63] op_sel:[0,1,0]
	v_pk_fma_f32 v[58:59], v[0:1], v[58:59], v[64:65] op_sel:[0,1,0]
	v_pk_fma_f32 v[62:63], v[2:3], v[48:49], v[66:67] op_sel:[0,1,0]
	v_pk_fma_f32 v[48:49], v[0:1], v[48:49], v[68:69] op_sel:[0,1,0]
	v_pk_fma_f32 v[64:65], v[2:3], v[16:17], v[70:71] op_sel:[0,1,0]
	v_pk_fma_f32 v[16:17], v[0:1], v[16:17], v[72:73] op_sel:[0,1,0]
	v_pk_fma_f32 v[6:7], v[0:1], v[8:9], v[6:7] op_sel:[0,1,0]
	v_add_co_u32_e32 v0, vcc, s5, v46
	v_pk_fma_f32 v[4:5], v[2:3], v[8:9], v[4:5] op_sel:[0,1,0]
	s_nop 0
	v_addc_co_u32_e32 v1, vcc, 0, v47, vcc
	s_waitcnt vmcnt(9)
	v_mov_b64_e32 v[0:1], v[104:105]
	v_mov_b64_e32 v[2:3], v[106:107]
	s_mov_b32 s5, 0x2a000
	v_pk_fma_f32 v[8:9], v[2:3], v[30:31], v[12:13] op_sel_hi:[1,0,1]
	v_pk_fma_f32 v[12:13], v[0:1], v[30:31], v[14:15] op_sel_hi:[1,0,1]
	v_pk_fma_f32 v[14:15], v[2:3], v[60:61], v[28:29] op_sel_hi:[1,0,1]
	v_pk_fma_f32 v[28:29], v[0:1], v[60:61], v[58:59] op_sel_hi:[1,0,1]
	v_pk_fma_f32 v[48:49], v[0:1], v[50:51], v[48:49] op_sel_hi:[1,0,1]
	v_pk_fma_f32 v[16:17], v[0:1], v[18:19], v[16:17] op_sel_hi:[1,0,1]
	v_pk_fma_f32 v[6:7], v[0:1], v[10:11], v[6:7] op_sel_hi:[1,0,1]
	v_add_co_u32_e32 v0, vcc, s5, v46
	v_pk_fma_f32 v[58:59], v[2:3], v[50:51], v[62:63] op_sel_hi:[1,0,1]
	s_nop 0
	v_addc_co_u32_e32 v1, vcc, 0, v47, vcc
	v_pk_fma_f32 v[62:63], v[2:3], v[18:19], v[64:65] op_sel_hi:[1,0,1]
	v_pk_fma_f32 v[4:5], v[2:3], v[10:11], v[4:5] op_sel_hi:[1,0,1]
	s_waitcnt vmcnt(8)
	v_mov_b64_e32 v[0:1], v[108:109]
	v_mov_b64_e32 v[2:3], v[110:111]
	v_mov_b32_e32 v10, v31
	s_mov_b32 s5, 0x30000
	v_pk_fma_f32 v[8:9], v[2:3], v[10:11], v[8:9] op_sel_hi:[1,0,1]
	v_pk_fma_f32 v[12:13], v[0:1], v[10:11], v[12:13] op_sel_hi:[1,0,1]
	v_mov_b32_e32 v10, v61
	v_pk_fma_f32 v[14:15], v[2:3], v[10:11], v[14:15] op_sel_hi:[1,0,1]
	v_pk_fma_f32 v[28:29], v[0:1], v[10:11], v[28:29] op_sel_hi:[1,0,1]
	v_mov_b32_e32 v10, v51
	v_pk_fma_f32 v[30:31], v[2:3], v[10:11], v[58:59] op_sel_hi:[1,0,1]
	v_pk_fma_f32 v[48:49], v[0:1], v[10:11], v[48:49] op_sel_hi:[1,0,1]
	v_mov_b32_e32 v10, v19
	v_pk_fma_f32 v[50:51], v[2:3], v[10:11], v[62:63] op_sel_hi:[1,0,1]
	v_pk_fma_f32 v[58:59], v[0:1], v[10:11], v[16:17] op_sel_hi:[1,0,1]
	v_mov_b32_e32 v10, v11
	v_pk_fma_f32 v[62:63], v[0:1], v[10:11], v[6:7] op_sel_hi:[1,0,1]
	v_add_co_u32_e32 v0, vcc, s5, v46
	v_pk_fma_f32 v[60:61], v[2:3], v[10:11], v[4:5] op_sel_hi:[1,0,1]
	s_nop 0
	v_addc_co_u32_e32 v1, vcc, 0, v47, vcc
	s_waitcnt vmcnt(7)
	v_mov_b64_e32 v[16:17], v[112:113]
	v_mov_b64_e32 v[18:19], v[114:115]
	ds_read_b128 v[0:3], v43 offset:1056
	ds_read_b128 v[4:7], v43 offset:2080
	s_mov_b32 s5, 0x36000
	v_pk_fma_f32 v[64:65], v[18:19], v[24:25], v[8:9] op_sel_hi:[1,0,1]
	v_pk_fma_f32 v[66:67], v[16:17], v[24:25], v[12:13] op_sel_hi:[1,0,1]
	s_waitcnt lgkmcnt(1)
	v_pk_fma_f32 v[68:69], v[18:19], v[0:1], v[14:15] op_sel_hi:[1,0,1]
	ds_read_b128 v[8:11], v43 offset:3104
	ds_read_b128 v[12:15], v43 offset:4128
	v_pk_fma_f32 v[28:29], v[16:17], v[0:1], v[28:29] op_sel_hi:[1,0,1]
	s_waitcnt lgkmcnt(2)
	v_pk_fma_f32 v[48:49], v[16:17], v[4:5], v[48:49] op_sel_hi:[1,0,1]
	v_pk_fma_f32 v[30:31], v[18:19], v[4:5], v[30:31] op_sel_hi:[1,0,1]
	s_waitcnt lgkmcnt(1)
	v_pk_fma_f32 v[58:59], v[16:17], v[8:9], v[58:59] op_sel_hi:[1,0,1]
	s_waitcnt lgkmcnt(0)
	v_pk_fma_f32 v[62:63], v[16:17], v[12:13], v[62:63] op_sel_hi:[1,0,1]
	v_add_co_u32_e32 v16, vcc, s5, v46
	v_pk_fma_f32 v[50:51], v[18:19], v[8:9], v[50:51] op_sel_hi:[1,0,1]
	s_nop 0
	v_addc_co_u32_e32 v17, vcc, 0, v47, vcc
	v_pk_fma_f32 v[60:61], v[18:19], v[12:13], v[60:61] op_sel_hi:[1,0,1]
	s_waitcnt vmcnt(6)
	v_mov_b64_e32 v[16:17], v[116:117]
	v_mov_b64_e32 v[18:19], v[118:119]
	s_mov_b32 s5, 0x3c000
	v_pk_fma_f32 v[64:65], v[18:19], v[24:25], v[64:65] op_sel:[0,1,0]
	v_pk_fma_f32 v[24:25], v[16:17], v[24:25], v[66:67] op_sel:[0,1,0]
	v_pk_fma_f32 v[66:67], v[18:19], v[0:1], v[68:69] op_sel:[0,1,0]
	v_pk_fma_f32 v[0:1], v[16:17], v[0:1], v[28:29] op_sel:[0,1,0]
	v_pk_fma_f32 v[28:29], v[18:19], v[4:5], v[30:31] op_sel:[0,1,0]
	v_pk_fma_f32 v[4:5], v[16:17], v[4:5], v[48:49] op_sel:[0,1,0]
	v_pk_fma_f32 v[30:31], v[18:19], v[8:9], v[50:51] op_sel:[0,1,0]
	v_pk_fma_f32 v[8:9], v[16:17], v[8:9], v[58:59] op_sel:[0,1,0]
	v_pk_fma_f32 v[48:49], v[18:19], v[12:13], v[60:61] op_sel:[0,1,0]
	v_pk_fma_f32 v[12:13], v[16:17], v[12:13], v[62:63] op_sel:[0,1,0]
	v_add_co_u32_e32 v16, vcc, s5, v46
	s_mov_b32 s5, 0x42000
	s_nop 0
	v_addc_co_u32_e32 v17, vcc, 0, v47, vcc
	s_waitcnt vmcnt(5)
	v_mov_b64_e32 v[16:17], v[120:121]
	v_mov_b64_e32 v[18:19], v[122:123]
	v_pk_fma_f32 v[50:51], v[18:19], v[26:27], v[64:65] op_sel_hi:[1,0,1]
	v_pk_fma_f32 v[64:65], v[16:17], v[10:11], v[8:9] op_sel_hi:[1,0,1]
	v_add_co_u32_e32 v8, vcc, s5, v46
	v_pk_fma_f32 v[60:61], v[18:19], v[6:7], v[28:29] op_sel_hi:[1,0,1]
	s_nop 0
	v_addc_co_u32_e32 v9, vcc, 0, v47, vcc
	v_pk_fma_f32 v[62:63], v[18:19], v[10:11], v[30:31] op_sel_hi:[1,0,1]
	s_waitcnt vmcnt(4)
	v_mov_b64_e32 v[28:29], v[124:125]
	v_mov_b64_e32 v[30:31], v[126:127]
	v_pk_fma_f32 v[24:25], v[16:17], v[26:27], v[24:25] op_sel_hi:[1,0,1]
	v_pk_fma_f32 v[58:59], v[18:19], v[2:3], v[66:67] op_sel_hi:[1,0,1]
	v_pk_fma_f32 v[0:1], v[16:17], v[2:3], v[0:1] op_sel_hi:[1,0,1]
	v_mov_b32_e32 v2, v27
	v_pk_fma_f32 v[4:5], v[16:17], v[6:7], v[4:5] op_sel_hi:[1,0,1]
	v_pk_fma_f32 v[48:49], v[18:19], v[14:15], v[48:49] op_sel_hi:[1,0,1]
	v_pk_fma_f32 v[12:13], v[16:17], v[14:15], v[12:13] op_sel_hi:[1,0,1]
	s_mov_b32 s5, 0x48000
	v_pk_fma_f32 v[26:27], v[30:31], v[2:3], v[50:51] op_sel_hi:[1,0,1]
	v_pk_fma_f32 v[24:25], v[28:29], v[2:3], v[24:25] op_sel_hi:[1,0,1]
	v_mov_b32_e32 v2, v3
	v_pk_fma_f32 v[50:51], v[30:31], v[2:3], v[58:59] op_sel_hi:[1,0,1]
	v_pk_fma_f32 v[58:59], v[28:29], v[2:3], v[0:1] op_sel_hi:[1,0,1]
	v_mov_b32_e32 v0, v7
	v_pk_fma_f32 v[16:17], v[30:31], v[0:1], v[60:61] op_sel_hi:[1,0,1]
	v_pk_fma_f32 v[18:19], v[28:29], v[0:1], v[4:5] op_sel_hi:[1,0,1]
	v_mov_b32_e32 v0, v11
	v_pk_fma_f32 v[8:9], v[30:31], v[0:1], v[62:63] op_sel_hi:[1,0,1]
	v_pk_fma_f32 v[10:11], v[28:29], v[0:1], v[64:65] op_sel_hi:[1,0,1]
	v_mov_b32_e32 v0, v15
	v_pk_fma_f32 v[4:5], v[30:31], v[0:1], v[48:49] op_sel_hi:[1,0,1]
	v_pk_fma_f32 v[6:7], v[28:29], v[0:1], v[12:13] op_sel_hi:[1,0,1]
	v_add_co_u32_e32 v0, vcc, s5, v46
	ds_read_b128 v[28:31], v43 offset:2096
	s_nop 0
	v_addc_co_u32_e32 v1, vcc, 0, v47, vcc
	s_waitcnt vmcnt(3)
	v_mov_b64_e32 v[0:1], v[128:129]
	v_mov_b64_e32 v[2:3], v[130:131]
	s_mov_b32 s5, 0x4e000
	v_pk_fma_f32 v[12:13], v[2:3], v[20:21], v[26:27] op_sel_hi:[1,0,1]
	v_pk_fma_f32 v[14:15], v[0:1], v[20:21], v[24:25] op_sel_hi:[1,0,1]
	ds_read_b128 v[24:27], v43 offset:1072
	s_waitcnt lgkmcnt(1)
	v_pk_fma_f32 v[62:63], v[2:3], v[28:29], v[16:17] op_sel_hi:[1,0,1]
	v_pk_fma_f32 v[64:65], v[0:1], v[28:29], v[18:19] op_sel_hi:[1,0,1]
	ds_read_b128 v[16:19], v43 offset:3120
	s_waitcnt lgkmcnt(1)
	v_pk_fma_f32 v[60:61], v[2:3], v[24:25], v[50:51] op_sel_hi:[1,0,1]
	ds_read_b128 v[48:51], v43 offset:4144
	v_pk_fma_f32 v[58:59], v[0:1], v[24:25], v[58:59] op_sel_hi:[1,0,1]
	s_waitcnt lgkmcnt(1)
	v_pk_fma_f32 v[10:11], v[0:1], v[16:17], v[10:11] op_sel_hi:[1,0,1]
	v_pk_fma_f32 v[8:9], v[2:3], v[16:17], v[8:9] op_sel_hi:[1,0,1]
	v_add_u32_e32 v43, 64, v43
	s_waitcnt lgkmcnt(0)
	v_pk_fma_f32 v[6:7], v[0:1], v[48:49], v[6:7] op_sel_hi:[1,0,1]
	v_add_co_u32_e32 v0, vcc, s5, v46
	v_pk_fma_f32 v[4:5], v[2:3], v[48:49], v[4:5] op_sel_hi:[1,0,1]
	s_nop 0
	v_addc_co_u32_e32 v1, vcc, 0, v47, vcc
	s_waitcnt vmcnt(2)
	v_mov_b64_e32 v[0:1], v[132:133]
	v_mov_b64_e32 v[2:3], v[134:135]
	s_mov_b32 s5, 0x54000
	v_pk_fma_f32 v[12:13], v[2:3], v[20:21], v[12:13] op_sel:[0,1,0]
	v_pk_fma_f32 v[14:15], v[0:1], v[20:21], v[14:15] op_sel:[0,1,0]
	v_pk_fma_f32 v[20:21], v[2:3], v[24:25], v[60:61] op_sel:[0,1,0]
	v_pk_fma_f32 v[24:25], v[0:1], v[24:25], v[58:59] op_sel:[0,1,0]
	v_pk_fma_f32 v[58:59], v[2:3], v[28:29], v[62:63] op_sel:[0,1,0]
	v_pk_fma_f32 v[28:29], v[0:1], v[28:29], v[64:65] op_sel:[0,1,0]
	v_pk_fma_f32 v[10:11], v[0:1], v[16:17], v[10:11] op_sel:[0,1,0]
	v_pk_fma_f32 v[6:7], v[0:1], v[48:49], v[6:7] op_sel:[0,1,0]
	v_add_co_u32_e32 v0, vcc, s5, v46
	v_pk_fma_f32 v[8:9], v[2:3], v[16:17], v[8:9] op_sel:[0,1,0]
	s_nop 0
	v_addc_co_u32_e32 v1, vcc, 0, v47, vcc
	v_pk_fma_f32 v[4:5], v[2:3], v[48:49], v[4:5] op_sel:[0,1,0]
	s_waitcnt vmcnt(1)
	v_mov_b64_e32 v[0:1], v[136:137]
	v_mov_b64_e32 v[2:3], v[138:139]
	s_mov_b32 s5, 0x5a000
	v_pk_fma_f32 v[14:15], v[0:1], v[22:23], v[14:15] op_sel_hi:[1,0,1]
	v_pk_fma_f32 v[16:17], v[2:3], v[26:27], v[20:21] op_sel_hi:[1,0,1]
	v_pk_fma_f32 v[20:21], v[0:1], v[26:27], v[24:25] op_sel_hi:[1,0,1]
	v_pk_fma_f32 v[28:29], v[0:1], v[30:31], v[28:29] op_sel_hi:[1,0,1]
	v_pk_fma_f32 v[60:61], v[0:1], v[18:19], v[10:11] op_sel_hi:[1,0,1]
	v_pk_fma_f32 v[64:65], v[0:1], v[50:51], v[6:7] op_sel_hi:[1,0,1]
	v_add_co_u32_e32 v0, vcc, s5, v46
	v_pk_fma_f32 v[12:13], v[2:3], v[22:23], v[12:13] op_sel_hi:[1,0,1]
	s_nop 0
	v_addc_co_u32_e32 v1, vcc, 0, v47, vcc
	s_waitcnt vmcnt(0)
	v_mov_b64_e32 v[46:47], v[140:141]
	v_mov_b64_e32 v[48:49], v[142:143]
	v_pk_fma_f32 v[62:63], v[2:3], v[50:51], v[4:5] op_sel_hi:[1,0,1]
	v_mov_b32_e32 v0, v23
	v_mov_b32_e32 v4, v27
	v_pk_fma_f32 v[24:25], v[2:3], v[30:31], v[58:59] op_sel_hi:[1,0,1]
	v_pk_fma_f32 v[58:59], v[2:3], v[18:19], v[8:9] op_sel_hi:[1,0,1]
	v_mov_b32_e32 v8, v31
	v_pk_fma_f32 v[2:3], v[48:49], v[0:1], v[12:13] op_sel_hi:[1,0,1]
	v_pk_fma_f32 v[6:7], v[48:49], v[4:5], v[16:17] op_sel_hi:[1,0,1]
	v_mov_b32_e32 v12, v19
	v_mov_b32_e32 v16, v51
	v_pk_fma_f32 v[0:1], v[46:47], v[0:1], v[14:15] op_sel_hi:[1,0,1]
	v_pk_fma_f32 v[4:5], v[46:47], v[4:5], v[20:21] op_sel_hi:[1,0,1]
	v_pk_fma_f32 v[10:11], v[48:49], v[8:9], v[24:25] op_sel_hi:[1,0,1]
	v_pk_fma_f32 v[8:9], v[46:47], v[8:9], v[28:29] op_sel_hi:[1,0,1]
	v_pk_fma_f32 v[14:15], v[48:49], v[12:13], v[58:59] op_sel_hi:[1,0,1]
	v_pk_fma_f32 v[12:13], v[46:47], v[12:13], v[60:61] op_sel_hi:[1,0,1]
	v_pk_fma_f32 v[18:19], v[48:49], v[16:17], v[62:63] op_sel_hi:[1,0,1]
	v_pk_fma_f32 v[16:17], v[46:47], v[16:17], v[64:65] op_sel_hi:[1,0,1]
	s_cbranch_scc0 .LBB0_531
	ds_write_b128 v55, v[0:3] offset:5120
	ds_write_b128 v55, v[4:7] offset:6144
	ds_write_b128 v55, v[8:11] offset:7168
	ds_write_b128 v55, v[12:15] offset:8192
	ds_write_b128 v55, v[16:19] offset:9216
	s_waitcnt lgkmcnt(0)
	s_barrier
	s_and_saveexec_b64 s[8:9], s[38:39]
	s_cbranch_execz .LBB0_526
	s_lshl_b32 s5, s11, 2
	s_add_i32 s4, s5, s4
	s_mul_i32 s11, s4, 5
	v_lshl_add_u64 v[0:1], s[6:7], 2, v[40:41]
	s_mov_b64 s[6:7], -1
	v_mov_b32_e32 v2, v34
	s_and_saveexec_b64 s[4:5], s[40:41]
	s_cbranch_execz .LBB0_537
	s_mov_b32 s12, s11
	s_mov_b64 s[6:7], 0
	v_mov_b32_e32 v4, v39
	v_mov_b64_e32 v[2:3], v[34:35]
